# norm: shift/scale vector loads issued with the row loads (one round trip per trip), shared between the two prompt rows
# speedup vs baseline: 1.0488x; 1.0029x over previous
.LBB0_1027:
	s_or_b64 exec, exec, s[52:53]
	v_lshrrev_b32_e32 v98, 10, v156
	s_and_b64 vcc, exec, s[42:43]
	v_cmp_lt_i32_e64 s[42:43], s91, v157
	v_lshl_add_u64 v[200:201], s[80:81], 0, v[160:161]
	v_add_u32_e32 v178, 1, v98
	v_readlane_b32 s96, v253, 40
	v_readlane_b32 s97, v253, 41
	s_nop 0
	s_and_b64 s[96:97], s[96:97], exec
	s_cbranch_scc0 .Lnh_nohoist
	v_cmp_lt_i32_e64 s[96:97], s91, v157
	v_mov_b64_e32 v[236:237], s[22:23]
	s_movk_i32 s30, 0x6000
	s_nop 0
	v_cndmask_b32_e64 v232, 0, v178, s[96:97]
	v_add_u32_e32 v232, s20, v232
	s_nop 0
	v_mad_u64_u32 v[250:251], s[12:13], v232, s30, v[236:237]
	s_nop 1
	v_lshl_add_u64 v[250:251], v[250:251], 0, v[0:1]
	s_nop 1
	global_load_dwordx4 v[234:237], v[250:251], off
	global_load_dwordx4 v[238:241], v[250:251], off offset:1024
	global_load_dwordx4 v[242:245], v[250:251], off offset:2048
	global_load_dwordx4 v[246:249], v[250:251], off offset:3072
	v_lshl_add_u64 v[232:233], v[250:251], 0, s[60:61]
	s_nop 1
	global_load_dwordx4 v[66:69], v[232:233], off
	global_load_dwordx4 v[70:73], v[232:233], off offset:1024
	global_load_dwordx4 v[74:77], v[232:233], off offset:2048
	global_load_dwordx4 v[78:81], v[232:233], off offset:3072
.Lnh_nohoist:
	s_cbranch_vccnz .LBB0_1033
	v_cndmask_b32_e64 v98, 0, v178, s[42:43]
	v_mov_b32_e32 v99, v1
	v_lshl_add_u64 v[98:99], s[16:17], 0, v[98:99]
	s_movk_i32 s30, 0x6000
	v_mad_u64_u32 v[100:101], s[12:13], v98, s30, v[154:155]
	v_mov_b32_e32 v98, v101
	v_mad_u64_u32 v[98:99], s[12:13], v99, s30, v[98:99]
	s_mov_b32 s12, 0x12cdc000
	s_nop 0
	v_add_co_u32_e32 v114, vcc, s12, v200
	v_mov_b32_e32 v101, v98
	s_nop 0
	v_addc_co_u32_e32 v115, vcc, 0, v201, vcc
	v_add_co_u32_e32 v116, vcc, 0x138dc000, v200
	s_nop 1
	v_addc_co_u32_e32 v117, vcc, 0, v201, vcc
	global_load_dwordx4 v[110:113], v[100:101], off
	global_load_dwordx4 v[106:109], v[100:101], off offset:1024
	global_load_dwordx4 v[102:105], v[100:101], off offset:2048
	s_nop 0
	global_load_dwordx4 v[98:101], v[100:101], off offset:3072
	s_nop 0
	global_load_dwordx2 v[126:127], v[114:115], off
	global_load_dwordx2 v[122:123], v[114:115], off offset:512
	global_load_dwordx2 v[118:119], v[114:115], off offset:1024
	s_nop 0
	global_load_dwordx2 v[114:115], v[114:115], off offset:1536
	s_nop 0
	global_load_dwordx2 v[128:129], v[116:117], off
	global_load_dwordx2 v[124:125], v[116:117], off offset:512
	global_load_dwordx2 v[120:121], v[116:117], off offset:1024
	s_nop 0
	global_load_dwordx2 v[116:117], v[116:117], off offset:1536
	s_and_saveexec_b64 s[42:43], s[40:41]
	s_cbranch_execz .LBB0_1030
	v_lshrrev_b32_e32 v10, 10, v198
	v_add_u32_e32 v10, 1, v10
	v_cmp_lt_i32_e32 vcc, s91, v196
	v_mov_b32_e32 v11, v1
	v_ashrrev_i32_e32 v197, 31, v196
	v_cndmask_b32_e32 v10, 0, v10, vcc
	v_lshl_add_u64 v[10:11], s[16:17], 0, v[10:11]
	v_mad_u64_u32 v[38:39], s[12:13], v10, s30, v[154:155]
	v_lshlrev_b64 v[12:13], 11, v[196:197]
	v_mov_b32_e32 v10, v39
	v_lshl_add_u64 v[188:189], s[0:1], 0, v[12:13]
	v_lshl_add_u64 v[190:191], s[18:19], 0, v[12:13]
	v_mad_u64_u32 v[10:11], s[12:13], v11, s30, v[10:11]
	v_mov_b32_e32 v165, v1
	v_mov_b32_e32 v167, v1
	v_mov_b32_e32 v169, v1
	v_mov_b32_e32 v39, v10
	v_lshl_add_u64 v[30:31], v[188:189], 0, v[164:165]
	v_lshl_add_u64 v[32:33], v[190:191], 0, v[164:165]
	v_lshl_add_u64 v[40:41], v[188:189], 0, v[166:167]
	v_lshl_add_u64 v[186:187], v[190:191], 0, v[166:167]
	v_lshl_add_u64 v[192:193], v[188:189], 0, v[168:169]
	v_lshl_add_u64 v[194:195], v[190:191], 0, v[168:169]
	v_mov_b32_e32 v177, v1
	global_load_dwordx4 v[10:13], v[38:39], off
	global_load_dwordx4 v[14:17], v[38:39], off offset:1024
	global_load_dwordx2 v[180:181], v[30:31], off
	global_load_dwordx2 v[184:185], v[32:33], off
	global_load_dwordx2 v[182:183], v[40:41], off
	s_nop 0
	global_load_dwordx2 v[186:187], v[186:187], off
	s_nop 0
	global_load_dwordx4 v[30:33], v[38:39], off offset:2048
	s_nop 0
	global_load_dwordx4 v[38:41], v[38:39], off offset:3072
	v_lshl_add_u64 v[228:229], v[188:189], 0, v[176:177]
	v_lshl_add_u64 v[230:231], v[190:191], 0, v[176:177]
	global_load_dwordx2 v[188:189], v[192:193], off
	s_nop 0
	global_load_dwordx2 v[192:193], v[194:195], off
	global_load_dwordx2 v[190:191], v[228:229], off
	s_nop 0
	global_load_dwordx2 v[194:195], v[230:231], off

.LBB0_1033:
	v_readlane_b32 s12, v253, 40
	v_readlane_b32 s13, v253, 41
	s_andn2_b64 vcc, exec, s[12:13]
	v_mov_b64_e32 v[114:115], v[146:147]
	v_cndmask_b32_e64 v98, 0, 1, s[12:13]
	v_cmp_ne_u32_e64 s[42:43], 1, v98
	v_mov_b64_e32 v[102:103], v[144:145]
	v_mov_b64_e32 v[100:101], v[142:143]
	v_mov_b64_e32 v[98:99], v[140:141]
	s_cbranch_vccnz .LBB0_1035
	s_branch .Lnh_sc0done

.Lnh_sc0done:
	s_and_saveexec_b64 s[52:53], s[40:41]
	s_cbranch_execz .LBB0_1041
	s_and_b64 vcc, exec, s[42:43]
	s_mov_b64 s[54:55], -1
	s_cbranch_vccnz .LBB0_1038
	s_waitcnt vmcnt(0)
	v_mov_b64_e32 v[114:115], v[234:235]
	v_mov_b64_e32 v[116:117], v[236:237]
	v_mov_b64_e32 v[118:119], v[238:239]
	v_mov_b64_e32 v[120:121], v[240:241]
	v_mov_b64_e32 v[122:123], v[242:243]
	v_mov_b64_e32 v[124:125], v[244:245]
	v_mov_b64_e32 v[126:127], v[246:247]
	v_mov_b64_e32 v[128:129], v[248:249]
	s_mov_b64 s[54:55], 0

.LBB0_1041:
	s_or_b64 exec, exec, s[52:53]
	s_waitcnt vmcnt(0)
	s_and_b64 vcc, exec, s[42:43]
	s_cbranch_vccnz .Lnh_nocopy
	v_mov_b64_e32 v[26:27], v[234:235]
	v_mov_b64_e32 v[28:29], v[236:237]
	v_mov_b64_e32 v[34:35], v[238:239]
	v_mov_b64_e32 v[36:37], v[240:241]
	v_mov_b64_e32 v[42:43], v[242:243]
	v_mov_b64_e32 v[44:45], v[244:245]
	v_mov_b64_e32 v[46:47], v[246:247]
	v_mov_b64_e32 v[48:49], v[248:249]
	v_mov_b64_e32 v[110:111], v[66:67]
	v_mov_b64_e32 v[112:113], v[68:69]
	v_mov_b64_e32 v[106:107], v[70:71]
	v_mov_b64_e32 v[108:109], v[72:73]
	v_mov_b64_e32 v[102:103], v[74:75]
	v_mov_b64_e32 v[104:105], v[76:77]
	v_mov_b64_e32 v[98:99], v[78:79]
	v_mov_b64_e32 v[100:101], v[80:81]
.Lnh_nocopy:
	v_mov_b32_e32 v116, v91
	v_mov_b32_e32 v117, v95
	v_mov_b32_e32 v114, v90
	v_mov_b32_e32 v115, v94
	v_pk_mul_f32 v[116:117], v[116:117], v[116:117]
	v_mov_b32_e32 v118, v83
	v_pk_fma_f32 v[114:115], v[114:115], v[114:115], v[116:117]
	v_mov_b32_e32 v116, v92
	v_mov_b32_e32 v117, v96
	v_pk_fma_f32 v[114:115], v[116:117], v[116:117], v[114:115]
	v_mov_b32_e32 v116, v93
	v_mov_b32_e32 v117, v97
	v_mov_b32_e32 v119, v87
	v_pk_fma_f32 v[114:115], v[116:117], v[116:117], v[114:115]
	v_mov_b32_e32 v116, v82
	v_mov_b32_e32 v117, v86
	v_pk_mul_f32 v[118:119], v[118:119], v[118:119]
	v_add_f32_e32 v0, v114, v115
	v_pk_fma_f32 v[116:117], v[116:117], v[116:117], v[118:119]
	v_mov_b32_e32 v118, v84
	v_mov_b32_e32 v119, v88
	v_pk_fma_f32 v[116:117], v[118:119], v[118:119], v[116:117]
	v_mov_b32_e32 v118, v85
	v_mov_b32_e32 v119, v89
	v_pk_fma_f32 v[116:117], v[118:119], v[118:119], v[116:117]
	s_nop 0
	v_add_f32_e32 v0, v117, v0
	v_add_f32_e32 v0, v116, v0
	s_waitcnt lgkmcnt(0)
	s_nop 1
	v_add_f32_dpp v114, v0, v0 quad_perm:[1,0,3,2] row_mask:0xf bank_mask:0xf
	s_nop 1
	v_add_f32_dpp v114, v114, v114 quad_perm:[2,3,0,1] row_mask:0xf bank_mask:0xf
	s_nop 1
	v_add_f32_dpp v114, v114, v114 row_ror:4 row_mask:0xf bank_mask:0xf
	s_nop 1
	v_add_f32_dpp v114, v114, v114 row_ror:8 row_mask:0xf bank_mask:0xf
	s_nop 1
	v_readlane_b32 s96, v114, 0
	v_readlane_b32 s97, v114, 16
	v_readlane_b32 s98, v114, 32
	v_readlane_b32 s99, v114, 48
	v_mov_b32_e32 v0, s96
	v_add_f32_e32 v0, s97, v0
	v_add_f32_e32 v0, s98, v0
	v_add_f32_e32 v0, s99, v0
	v_fmamk_f32 v0, v0, 0x3a800000, v203
	v_mul_f32_e32 v114, 0x4b800000, v0
	v_cmp_gt_f32_e32 vcc, s87, v0
	s_nop 1
	v_cndmask_b32_e32 v0, v0, v114, vcc
	v_rsq_f32_e32 v0, v0
	s_nop 0
	v_mul_f32_e32 v114, 0x45800000, v0
	v_cndmask_b32_e32 v178, v0, v114, vcc
	s_and_saveexec_b64 s[52:53], s[40:41]
	s_cbranch_execz .LBB0_1043
	v_mov_b32_e32 v116, v55
	v_mov_b32_e32 v117, v51
	v_mov_b32_e32 v114, v54
	v_mov_b32_e32 v115, v50
	v_pk_mul_f32 v[116:117], v[116:117], v[116:117]
	v_mov_b32_e32 v118, v63
	v_pk_fma_f32 v[114:115], v[114:115], v[114:115], v[116:117]
	v_mov_b32_e32 v116, v56
	v_mov_b32_e32 v117, v52
	v_pk_fma_f32 v[114:115], v[116:117], v[116:117], v[114:115]
	v_mov_b32_e32 v116, v57
	v_mov_b32_e32 v117, v53
	v_mov_b32_e32 v119, v59
	v_pk_fma_f32 v[114:115], v[116:117], v[116:117], v[114:115]
	v_mov_b32_e32 v116, v62
	v_mov_b32_e32 v117, v58
	v_pk_mul_f32 v[118:119], v[118:119], v[118:119]
	v_add_f32_e32 v0, v114, v115
	v_pk_fma_f32 v[116:117], v[116:117], v[116:117], v[118:119]
	v_mov_b32_e32 v118, v64
	v_mov_b32_e32 v119, v60
	v_pk_fma_f32 v[116:117], v[118:119], v[118:119], v[116:117]
	v_mov_b32_e32 v118, v65
	v_mov_b32_e32 v119, v61
	v_pk_fma_f32 v[116:117], v[118:119], v[118:119], v[116:117]
	s_nop 0
	v_add_f32_e32 v0, v117, v0
	v_add_f32_e32 v0, v116, v0
	s_waitcnt lgkmcnt(0)
	s_nop 1
	v_add_f32_dpp v114, v0, v0 quad_perm:[1,0,3,2] row_mask:0xf bank_mask:0xf
	s_nop 1
	v_add_f32_dpp v114, v114, v114 quad_perm:[2,3,0,1] row_mask:0xf bank_mask:0xf
	s_nop 1
	v_add_f32_dpp v114, v114, v114 row_ror:4 row_mask:0xf bank_mask:0xf
	s_nop 1
	v_add_f32_dpp v114, v114, v114 row_ror:8 row_mask:0xf bank_mask:0xf
	s_nop 1
	v_readlane_b32 s96, v114, 0
	v_readlane_b32 s97, v114, 16
	v_readlane_b32 s98, v114, 32
	v_readlane_b32 s99, v114, 48
	v_mov_b32_e32 v0, s96
	v_add_f32_e32 v0, s97, v0
	v_add_f32_e32 v0, s98, v0
	v_add_f32_e32 v0, s99, v0
	v_fmamk_f32 v0, v0, 0x3a800000, v203
	v_mul_f32_e32 v114, 0x4b800000, v0
	v_cmp_gt_f32_e32 vcc, s87, v0
	s_nop 1
	v_cndmask_b32_e32 v0, v0, v114, vcc
	v_rsq_f32_e32 v0, v0
	s_nop 0
	v_mul_f32_e32 v114, 0x45800000, v0
	v_cndmask_b32_e32 v179, v0, v114, vcc
